# v6 plus FoX unit epilogue: all 16 gate loads issued up front with one wait
# baseline (speedup 1.0000x reference)
; DI unsigned pk2(float lo, float hi) { f32x2_t v = {lo, hi}; bf16x2_t b = __builtin_convertvector(v, bf16x2_t); return __builtin_bit_cast(unsigned, b); }
; DI float bflo(unsigned w) { return __uint_as_float(w << 16); }
; DI float bfhi(unsigned w) { return __uint_as_float(w & 0xffff0000u); }
; DI float shx(float v, int m) { const int lane = tid_() & 63; return __builtin_bit_cast(float, __builtin_amdgcn_ds_bpermute((lane ^ m) << 2, __builtin_bit_cast(int, v))); }
; DI float sigmoidf_(float x) { return 1.f / (1.f + __expf(-x)); }
; template <int DQK, bool FOX>
; DI void attn_unit(const bf16_t* P, int pitch, int b, int qb, int qcol, int kcol, int vcol, bf16_t* Out, int opitch, int ocol, int gcol, const float* cum, lptr lds) {
;     ...
;     const float l = l_run + shx(l_run, 32);
;     const float inv = 1.f / l;
;     const size_t tok = tokbase + q0 + r;
; #pragma unroll
;     for (int d = 0; d < 4; ++d)
; #pragma unroll
;         for (int g = 0; g < 4; ++g) {
;             const int dv = 32 * d + 8 * g + 4 * h;
;             float v[4]; for (int e = 0; e < 4; ++e) v[e] = O[d][4 * g + e] * inv;
;             if (FOX) { const u32x2 gw = *(const u32x2*)(P + tok * pitch + gcol + dv);
;                 v[0] *= sigmoidf_(bflo(gw.x)); v[1] *= sigmoidf_(bfhi(gw.x)); v[2] *= sigmoidf_(bflo(gw.y)); v[3] *= sigmoidf_(bfhi(gw.y)); }
;             u32x2 o; o.x = pk2(v[0], v[1]); o.y = pk2(v[2], v[3]);
;             *(u32x2*)(Out + tok * opitch + ocol + dv) = o;
;         }
.LBB0_323:
	v_mov_b32_e32 v0, v194
	s_mov_b32 s43, s83
	v_lshlrev_b32_e32 v0, 2, v0
	v_bitop3_b32 v0, v0, s29, v199 bitop3:0x6c
	ds_bpermute_b32 v0, v0, v181
	s_waitcnt lgkmcnt(0)
	v_add_f32_e32 v0, v181, v0
	v_div_scale_f32 v66, s[2:3], v0, v0, 1.0
	v_rcp_f32_e32 v67, v66
	s_mov_b64 s[2:3], 0x1800
	v_fma_f32 v68, -v66, v67, 1.0
	v_fmac_f32_e32 v67, v68, v67
	v_div_scale_f32 v68, vcc, 1.0, v0, 1.0
	v_mul_f32_e32 v69, v68, v67
	v_fma_f32 v70, -v66, v69, v68
	v_fmac_f32_e32 v69, v70, v67
	v_fma_f32 v66, -v66, v69, v68
	v_div_fmas_f32 v66, v66, v67, v69
	v_div_fixup_f32 v66, v66, v0, 1.0
	v_lshl_add_u64 v[68:69], v[132:133], 0, s[2:3]
	v_lshlrev_b32_e32 v0, 1, v144
	v_lshl_add_u64 v[88:89], v[68:69], 0, v[0:1]
	global_load_dwordx2 v[90:91], v[88:89], off
	global_load_dwordx2 v[92:93], v[88:89], off offset:16
	global_load_dwordx2 v[94:95], v[88:89], off offset:32
	global_load_dwordx2 v[96:97], v[88:89], off offset:48
	global_load_dwordx2 v[98:99], v[88:89], off offset:64
	global_load_dwordx2 v[100:101], v[88:89], off offset:80
	global_load_dwordx2 v[102:103], v[88:89], off offset:96
	global_load_dwordx2 v[104:105], v[88:89], off offset:112
	global_load_dwordx2 v[106:107], v[88:89], off offset:128
	global_load_dwordx2 v[108:109], v[88:89], off offset:144
	global_load_dwordx2 v[110:111], v[88:89], off offset:160
	global_load_dwordx2 v[112:113], v[88:89], off offset:176
	global_load_dwordx2 v[114:115], v[88:89], off offset:192
	global_load_dwordx2 v[116:117], v[88:89], off offset:208
	global_load_dwordx2 v[118:119], v[88:89], off offset:224
	global_load_dwordx2 v[120:121], v[88:89], off offset:240
	v_lshlrev_b64 v[70:71], 11, v[130:131]
	v_lshl_add_u64 v[70:71], s[24:25], 0, v[70:71]
	v_lshl_add_u64 v[70:71], v[70:71], 0, s[42:43]
	s_waitcnt vmcnt(0)
	v_mov_b32_e32 v72, v90
	v_mov_b32_e32 v73, v91
	v_lshlrev_b32_e32 v67, 16, v72
	v_mul_f32_e32 v67, 0xbfb8aa3b, v67
	v_exp_f32_e32 v74, v67
	v_and_b32_e32 v67, 0xffff0000, v72
	v_mul_f32_e32 v67, 0xbfb8aa3b, v67
	v_exp_f32_e32 v75, v67
	v_pk_mul_f32 v[50:51], v[50:51], v[66:67] op_sel_hi:[1,0]
	v_pk_add_f32 v[74:75], v[74:75], 1.0 op_sel_hi:[1,0]
	s_nop 0
	v_div_scale_f32 v67, s[2:3], v75, v75, 1.0
	v_rcp_f32_e32 v72, v67
	s_nop 0
	v_fma_f32 v76, -v67, v72, 1.0
	v_fmac_f32_e32 v72, v76, v72
	v_div_scale_f32 v76, vcc, 1.0, v75, 1.0
	v_mul_f32_e32 v77, v76, v72
	v_fma_f32 v78, -v67, v77, v76
	v_fmac_f32_e32 v77, v78, v72
	v_fma_f32 v67, -v67, v77, v76
	v_div_fmas_f32 v67, v67, v72, v77
	v_div_fixup_f32 v75, v67, v75, 1.0
	v_div_scale_f32 v67, s[2:3], v74, v74, 1.0
	v_rcp_f32_e32 v72, v67
	s_nop 0
	v_fma_f32 v76, -v67, v72, 1.0
	v_fmac_f32_e32 v72, v76, v72
	v_div_scale_f32 v76, vcc, 1.0, v74, 1.0
	v_mul_f32_e32 v77, v76, v72
	v_fma_f32 v78, -v67, v77, v76
	v_fmac_f32_e32 v77, v78, v72
	v_fma_f32 v67, -v67, v77, v76
	v_div_fmas_f32 v67, v67, v72, v77
	v_div_fixup_f32 v74, v67, v74, 1.0
	v_lshlrev_b32_e32 v67, 16, v73
	v_mul_f32_e32 v67, 0xbfb8aa3b, v67
	v_exp_f32_e32 v72, v67
	v_and_b32_e32 v67, 0xffff0000, v73
	v_mul_f32_e32 v67, 0xbfb8aa3b, v67
	v_exp_f32_e32 v73, v67
	v_pk_mul_f32 v[52:53], v[52:53], v[66:67] op_sel_hi:[1,0]
	v_pk_mul_f32 v[50:51], v[50:51], v[74:75]
	v_pk_add_f32 v[72:73], v[72:73], 1.0 op_sel_hi:[1,0]
	s_nop 0
	v_div_scale_f32 v67, s[2:3], v73, v73, 1.0
	v_rcp_f32_e32 v74, v67
	s_nop 0
	v_fma_f32 v75, -v67, v74, 1.0
	v_fmac_f32_e32 v74, v75, v74
	v_div_scale_f32 v75, vcc, 1.0, v73, 1.0
	v_mul_f32_e32 v76, v75, v74
	v_fma_f32 v77, -v67, v76, v75
	v_fmac_f32_e32 v76, v77, v74
	v_fma_f32 v67, -v67, v76, v75
	v_div_fmas_f32 v67, v67, v74, v76
	v_div_fixup_f32 v73, v67, v73, 1.0
	v_div_scale_f32 v67, s[2:3], v72, v72, 1.0
	v_rcp_f32_e32 v74, v67
	s_nop 0
	v_fma_f32 v75, -v67, v74, 1.0
	v_fmac_f32_e32 v74, v75, v74
	v_div_scale_f32 v75, vcc, 1.0, v72, 1.0
	v_mul_f32_e32 v76, v75, v74
	v_fma_f32 v77, -v67, v76, v75
	v_fmac_f32_e32 v76, v77, v74
	v_fma_f32 v67, -v67, v76, v75
	v_div_fmas_f32 v67, v67, v74, v76
	v_div_fixup_f32 v72, v67, v72, 1.0
	v_pk_mul_f32 v[52:53], v[52:53], v[72:73]
	v_cvt_pk_bf16_f32 v72, v50, v51
	v_cvt_pk_bf16_f32 v73, v52, v53
	v_or_b32_e32 v52, 16, v0
	v_mov_b32_e32 v53, v1
	v_lshl_add_u64 v[52:53], v[68:69], 0, v[52:53]
	v_mov_b32_e32 v52, v92
	v_mov_b32_e32 v53, v93
	v_lshl_add_u64 v[50:51], v[70:71], 0, v[0:1]
	global_store_dwordx2 v[50:51], v[72:73], off
	v_lshlrev_b32_e32 v67, 16, v52
	v_and_b32_e32 v52, 0xffff0000, v52
	v_mul_f32_e32 v67, 0xbfb8aa3b, v67
	v_mul_f32_e32 v52, 0xbfb8aa3b, v52
	v_exp_f32_e32 v70, v67
	v_exp_f32_e32 v71, v52
	v_pk_mul_f32 v[54:55], v[54:55], v[66:67] op_sel_hi:[1,0]
	v_pk_add_f32 v[70:71], v[70:71], 1.0 op_sel_hi:[1,0]
	s_nop 0
	v_div_scale_f32 v52, s[2:3], v71, v71, 1.0
	v_rcp_f32_e32 v67, v52
	s_nop 0
	v_fma_f32 v72, -v52, v67, 1.0
	v_fmac_f32_e32 v67, v72, v67
	v_div_scale_f32 v72, vcc, 1.0, v71, 1.0
	v_mul_f32_e32 v73, v72, v67
	v_fma_f32 v74, -v52, v73, v72
	v_fmac_f32_e32 v73, v74, v67
	v_fma_f32 v52, -v52, v73, v72
	v_div_fmas_f32 v52, v52, v67, v73
	v_div_fixup_f32 v71, v52, v71, 1.0
	v_div_scale_f32 v52, s[2:3], v70, v70, 1.0
	v_rcp_f32_e32 v67, v52
	s_nop 0
	v_fma_f32 v72, -v52, v67, 1.0
	v_fmac_f32_e32 v67, v72, v67
	v_div_scale_f32 v72, vcc, 1.0, v70, 1.0
	v_mul_f32_e32 v73, v72, v67
	v_fma_f32 v74, -v52, v73, v72
	v_fmac_f32_e32 v73, v74, v67
	v_fma_f32 v52, -v52, v73, v72
	v_div_fmas_f32 v52, v52, v67, v73
	v_div_fixup_f32 v70, v52, v70, 1.0
	v_lshlrev_b32_e32 v52, 16, v53
	v_and_b32_e32 v53, 0xffff0000, v53
	v_mul_f32_e32 v52, 0xbfb8aa3b, v52
	v_mul_f32_e32 v53, 0xbfb8aa3b, v53
	v_exp_f32_e32 v52, v52
	v_exp_f32_e32 v53, v53
	v_pk_mul_f32 v[56:57], v[56:57], v[66:67] op_sel_hi:[1,0]
	v_pk_mul_f32 v[54:55], v[54:55], v[70:71]
; DI unsigned pk2(float lo, float hi) { f32x2_t v = {lo, hi}; bf16x2_t b = __builtin_convertvector(v, bf16x2_t); return __builtin_bit_cast(unsigned, b); }
; DI float bflo(unsigned w) { return __uint_as_float(w << 16); }
; DI float bfhi(unsigned w) { return __uint_as_float(w & 0xffff0000u); }
; DI float sigmoidf_(float x) { return 1.f / (1.f + __expf(-x)); }
; template <int DQK, bool FOX>
; DI void attn_unit(const bf16_t* P, int pitch, int b, int qb, int qcol, int kcol, int vcol, bf16_t* Out, int opitch, int ocol, int gcol, const float* cum, lptr lds) {
;     ...
;     for (int d = 0; d < 4; ++d)
; #pragma unroll
;         for (int g = 0; g < 4; ++g) {
;             const int dv = 32 * d + 8 * g + 4 * h;
;             float v[4]; for (int e = 0; e < 4; ++e) v[e] = O[d][4 * g + e] * inv;
;             if (FOX) { const u32x2 gw = *(const u32x2*)(P + tok * pitch + gcol + dv);
;                 v[0] *= sigmoidf_(bflo(gw.x)); v[1] *= sigmoidf_(bfhi(gw.x)); v[2] *= sigmoidf_(bflo(gw.y)); v[3] *= sigmoidf_(bfhi(gw.y)); }
;             u32x2 o; o.x = pk2(v[0], v[1]); o.y = pk2(v[2], v[3]);
;             *(u32x2*)(Out + tok * opitch + ocol + dv) = o;
	v_pk_add_f32 v[52:53], v[52:53], 1.0 op_sel_hi:[1,0]
	s_nop 0
	v_div_scale_f32 v67, s[2:3], v53, v53, 1.0
	v_rcp_f32_e32 v70, v67
	v_cvt_pk_bf16_f32 v54, v54, v55
	v_fma_f32 v71, -v67, v70, 1.0
	v_fmac_f32_e32 v70, v71, v70
	v_div_scale_f32 v71, vcc, 1.0, v53, 1.0
	v_mul_f32_e32 v72, v71, v70
	v_fma_f32 v73, -v67, v72, v71
	v_fmac_f32_e32 v72, v73, v70
	v_fma_f32 v67, -v67, v72, v71
	v_div_fmas_f32 v67, v67, v70, v72
	v_div_fixup_f32 v53, v67, v53, 1.0
	v_div_scale_f32 v67, s[2:3], v52, v52, 1.0
	v_rcp_f32_e32 v70, v67
	s_nop 0
	v_fma_f32 v71, -v67, v70, 1.0
	v_fmac_f32_e32 v70, v71, v70
	v_div_scale_f32 v71, vcc, 1.0, v52, 1.0
	v_mul_f32_e32 v72, v71, v70
	v_fma_f32 v73, -v67, v72, v71
	v_fmac_f32_e32 v72, v73, v70
	v_fma_f32 v67, -v67, v72, v71
	v_div_fmas_f32 v67, v67, v70, v72
	v_div_fixup_f32 v52, v67, v52, 1.0
	v_pk_mul_f32 v[52:53], v[56:57], v[52:53]
	v_pk_mul_f32 v[56:57], v[58:59], v[66:67] op_sel_hi:[1,0]
	v_cvt_pk_bf16_f32 v55, v52, v53
	v_or_b32_e32 v52, 32, v0
	v_mov_b32_e32 v53, v1
	v_lshl_add_u64 v[52:53], v[68:69], 0, v[52:53]
	v_mov_b32_e32 v52, v94
	v_mov_b32_e32 v53, v95
	s_nop 0
	global_store_dwordx2 v[50:51], v[54:55], off offset:16
	v_lshlrev_b32_e32 v54, 16, v52
	v_and_b32_e32 v52, 0xffff0000, v52
	v_mul_f32_e32 v54, 0xbfb8aa3b, v54
	v_mul_f32_e32 v52, 0xbfb8aa3b, v52
	v_exp_f32_e32 v54, v54
	v_exp_f32_e32 v55, v52
	s_nop 0
	v_pk_add_f32 v[54:55], v[54:55], 1.0 op_sel_hi:[1,0]
	s_nop 0
	v_div_scale_f32 v52, s[2:3], v55, v55, 1.0
	v_rcp_f32_e32 v58, v52
	s_nop 0
	v_fma_f32 v59, -v52, v58, 1.0
	v_fmac_f32_e32 v58, v59, v58
	v_div_scale_f32 v59, vcc, 1.0, v55, 1.0
	v_mul_f32_e32 v67, v59, v58
	v_fma_f32 v70, -v52, v67, v59
	v_fmac_f32_e32 v67, v70, v58
	v_fma_f32 v52, -v52, v67, v59
	v_div_fmas_f32 v52, v52, v58, v67
	v_div_fixup_f32 v55, v52, v55, 1.0
	v_div_scale_f32 v52, s[2:3], v54, v54, 1.0
	v_rcp_f32_e32 v58, v52
	s_nop 0
	v_fma_f32 v59, -v52, v58, 1.0
	v_fmac_f32_e32 v58, v59, v58
	v_div_scale_f32 v59, vcc, 1.0, v54, 1.0
	v_mul_f32_e32 v67, v59, v58
	v_fma_f32 v70, -v52, v67, v59
	v_fmac_f32_e32 v67, v70, v58
	v_fma_f32 v52, -v52, v67, v59
	v_div_fmas_f32 v52, v52, v58, v67
	v_div_fixup_f32 v54, v52, v54, 1.0
	v_lshlrev_b32_e32 v52, 16, v53
	v_and_b32_e32 v53, 0xffff0000, v53
	v_mul_f32_e32 v52, 0xbfb8aa3b, v52
	v_mul_f32_e32 v53, 0xbfb8aa3b, v53
	v_exp_f32_e32 v52, v52
	v_exp_f32_e32 v53, v53
	v_pk_mul_f32 v[54:55], v[56:57], v[54:55]
	v_pk_mul_f32 v[56:57], v[60:61], v[66:67] op_sel_hi:[1,0]
	v_cvt_pk_bf16_f32 v54, v54, v55
	v_pk_add_f32 v[52:53], v[52:53], 1.0 op_sel_hi:[1,0]
	s_nop 0
	v_div_scale_f32 v58, s[2:3], v53, v53, 1.0
	v_rcp_f32_e32 v59, v58
	s_nop 0
	v_fma_f32 v60, -v58, v59, 1.0
	v_fmac_f32_e32 v59, v60, v59
	v_div_scale_f32 v60, vcc, 1.0, v53, 1.0
	v_mul_f32_e32 v61, v60, v59
	v_fma_f32 v67, -v58, v61, v60
	v_fmac_f32_e32 v61, v67, v59
	v_fma_f32 v58, -v58, v61, v60
	v_div_fmas_f32 v58, v58, v59, v61
	v_div_fixup_f32 v53, v58, v53, 1.0
	v_div_scale_f32 v58, s[2:3], v52, v52, 1.0
	v_rcp_f32_e32 v59, v58
	s_nop 0
	v_fma_f32 v60, -v58, v59, 1.0
	v_fmac_f32_e32 v59, v60, v59
	v_div_scale_f32 v60, vcc, 1.0, v52, 1.0
	v_mul_f32_e32 v61, v60, v59
	v_fma_f32 v67, -v58, v61, v60
	v_fmac_f32_e32 v61, v67, v59
	v_fma_f32 v58, -v58, v61, v60
	v_div_fmas_f32 v58, v58, v59, v61
	v_div_fixup_f32 v52, v58, v52, 1.0
	v_pk_mul_f32 v[52:53], v[56:57], v[52:53]
	v_pk_mul_f32 v[56:57], v[62:63], v[66:67] op_sel_hi:[1,0]
	v_cvt_pk_bf16_f32 v55, v52, v53
	v_or_b32_e32 v52, 48, v0
	v_mov_b32_e32 v53, v1
	v_lshl_add_u64 v[52:53], v[68:69], 0, v[52:53]
	v_mov_b32_e32 v52, v96
	v_mov_b32_e32 v53, v97
	v_pk_mul_f32 v[34:35], v[34:35], v[66:67] op_sel_hi:[1,0]
	global_store_dwordx2 v[50:51], v[54:55], off offset:32
	v_pk_mul_f32 v[36:37], v[36:37], v[66:67] op_sel_hi:[1,0]
	v_pk_mul_f32 v[38:39], v[38:39], v[66:67] op_sel_hi:[1,0]
	v_pk_mul_f32 v[18:19], v[18:19], v[66:67] op_sel_hi:[1,0]
	v_pk_mul_f32 v[20:21], v[20:21], v[66:67] op_sel_hi:[1,0]
	v_pk_mul_f32 v[22:23], v[22:23], v[66:67] op_sel_hi:[1,0]
	v_pk_mul_f32 v[2:3], v[2:3], v[66:67] op_sel_hi:[1,0]
	v_pk_mul_f32 v[4:5], v[4:5], v[66:67] op_sel_hi:[1,0]
	v_pk_mul_f32 v[6:7], v[6:7], v[66:67] op_sel_hi:[1,0]
	v_lshlrev_b32_e32 v54, 16, v52
	v_and_b32_e32 v52, 0xffff0000, v52
	v_mul_f32_e32 v54, 0xbfb8aa3b, v54
	v_mul_f32_e32 v52, 0xbfb8aa3b, v52
	v_exp_f32_e32 v54, v54
	v_exp_f32_e32 v55, v52
	s_nop 0
	v_pk_add_f32 v[54:55], v[54:55], 1.0 op_sel_hi:[1,0]
	s_nop 0
	v_div_scale_f32 v52, s[2:3], v55, v55, 1.0
	v_rcp_f32_e32 v58, v52
	s_nop 0
	v_fma_f32 v59, -v52, v58, 1.0
	v_fmac_f32_e32 v58, v59, v58
	v_div_scale_f32 v59, vcc, 1.0, v55, 1.0
	v_mul_f32_e32 v60, v59, v58
	v_fma_f32 v61, -v52, v60, v59
	v_fmac_f32_e32 v60, v61, v58
	v_fma_f32 v52, -v52, v60, v59
	v_div_fmas_f32 v52, v52, v58, v60
	v_div_fixup_f32 v55, v52, v55, 1.0
	v_div_scale_f32 v52, s[2:3], v54, v54, 1.0
	v_rcp_f32_e32 v58, v52
	s_nop 0
	v_fma_f32 v59, -v52, v58, 1.0
	v_fmac_f32_e32 v58, v59, v58
	v_div_scale_f32 v59, vcc, 1.0, v54, 1.0
	v_mul_f32_e32 v60, v59, v58
	v_fma_f32 v61, -v52, v60, v59
	v_fmac_f32_e32 v60, v61, v58
	v_fma_f32 v52, -v52, v60, v59
	v_div_fmas_f32 v52, v52, v58, v60
	v_div_fixup_f32 v54, v52, v54, 1.0
	v_lshlrev_b32_e32 v52, 16, v53
	v_and_b32_e32 v53, 0xffff0000, v53
	v_mul_f32_e32 v52, 0xbfb8aa3b, v52
	v_mul_f32_e32 v53, 0xbfb8aa3b, v53
	v_exp_f32_e32 v52, v52
	v_exp_f32_e32 v53, v53
	v_pk_mul_f32 v[54:55], v[56:57], v[54:55]
	v_pk_mul_f32 v[56:57], v[64:65], v[66:67] op_sel_hi:[1,0]
	v_cvt_pk_bf16_f32 v54, v54, v55
	v_pk_add_f32 v[52:53], v[52:53], 1.0 op_sel_hi:[1,0]
	s_nop 0
	v_div_scale_f32 v58, s[2:3], v53, v53, 1.0
	v_rcp_f32_e32 v59, v58
	s_nop 0
	v_fma_f32 v60, -v58, v59, 1.0
; DI unsigned pk2(float lo, float hi) { f32x2_t v = {lo, hi}; bf16x2_t b = __builtin_convertvector(v, bf16x2_t); return __builtin_bit_cast(unsigned, b); }
; DI float bflo(unsigned w) { return __uint_as_float(w << 16); }
; DI float bfhi(unsigned w) { return __uint_as_float(w & 0xffff0000u); }
; DI float sigmoidf_(float x) { return 1.f / (1.f + __expf(-x)); }
; template <int DQK, bool FOX>
; DI void attn_unit(const bf16_t* P, int pitch, int b, int qb, int qcol, int kcol, int vcol, bf16_t* Out, int opitch, int ocol, int gcol, const float* cum, lptr lds) {
;     ...
;     for (int d = 0; d < 4; ++d)
; #pragma unroll
;         for (int g = 0; g < 4; ++g) {
;             const int dv = 32 * d + 8 * g + 4 * h;
;             float v[4]; for (int e = 0; e < 4; ++e) v[e] = O[d][4 * g + e] * inv;
;             if (FOX) { const u32x2 gw = *(const u32x2*)(P + tok * pitch + gcol + dv);
;                 v[0] *= sigmoidf_(bflo(gw.x)); v[1] *= sigmoidf_(bfhi(gw.x)); v[2] *= sigmoidf_(bflo(gw.y)); v[3] *= sigmoidf_(bfhi(gw.y)); }
;             u32x2 o; o.x = pk2(v[0], v[1]); o.y = pk2(v[2], v[3]);
;             *(u32x2*)(Out + tok * opitch + ocol + dv) = o;
	v_fmac_f32_e32 v59, v60, v59
	v_div_scale_f32 v60, vcc, 1.0, v53, 1.0
	v_mul_f32_e32 v61, v60, v59
	v_fma_f32 v62, -v58, v61, v60
	v_fmac_f32_e32 v61, v62, v59
	v_fma_f32 v58, -v58, v61, v60
	v_div_fmas_f32 v58, v58, v59, v61
	v_div_fixup_f32 v53, v58, v53, 1.0
	v_div_scale_f32 v58, s[2:3], v52, v52, 1.0
	v_rcp_f32_e32 v59, v58
	s_nop 0
	v_fma_f32 v60, -v58, v59, 1.0
	v_fmac_f32_e32 v59, v60, v59
	v_div_scale_f32 v60, vcc, 1.0, v52, 1.0
	v_mul_f32_e32 v61, v60, v59
	v_fma_f32 v62, -v58, v61, v60
	v_fmac_f32_e32 v61, v62, v59
	v_fma_f32 v58, -v58, v61, v60
	v_div_fmas_f32 v58, v58, v59, v61
	v_div_fixup_f32 v52, v58, v52, 1.0
	v_pk_mul_f32 v[52:53], v[56:57], v[52:53]
	s_nop 0
	v_cvt_pk_bf16_f32 v55, v52, v53
	v_or_b32_e32 v52, 64, v0
	v_mov_b32_e32 v53, v1
	v_lshl_add_u64 v[52:53], v[68:69], 0, v[52:53]
	v_mov_b32_e32 v52, v98
	v_mov_b32_e32 v53, v99
	s_nop 0
	global_store_dwordx2 v[50:51], v[54:55], off offset:48
	v_lshlrev_b32_e32 v54, 16, v52
	v_and_b32_e32 v52, 0xffff0000, v52
	v_mul_f32_e32 v54, 0xbfb8aa3b, v54
	v_mul_f32_e32 v52, 0xbfb8aa3b, v52
	v_exp_f32_e32 v54, v54
	v_exp_f32_e32 v55, v52
	s_nop 0
	v_pk_add_f32 v[54:55], v[54:55], 1.0 op_sel_hi:[1,0]
	s_nop 0
	v_div_scale_f32 v52, s[2:3], v55, v55, 1.0
	v_rcp_f32_e32 v56, v52
	s_nop 0
	v_fma_f32 v57, -v52, v56, 1.0
	v_fmac_f32_e32 v56, v57, v56
	v_div_scale_f32 v57, vcc, 1.0, v55, 1.0
	v_mul_f32_e32 v58, v57, v56
	v_fma_f32 v59, -v52, v58, v57
	v_fmac_f32_e32 v58, v59, v56
	v_fma_f32 v52, -v52, v58, v57
	v_div_fmas_f32 v52, v52, v56, v58
	v_div_fixup_f32 v55, v52, v55, 1.0
	v_div_scale_f32 v52, s[2:3], v54, v54, 1.0
	v_rcp_f32_e32 v56, v52
	s_nop 0
	v_fma_f32 v57, -v52, v56, 1.0
	v_fmac_f32_e32 v56, v57, v56
	v_div_scale_f32 v57, vcc, 1.0, v54, 1.0
	v_mul_f32_e32 v58, v57, v56
	v_fma_f32 v59, -v52, v58, v57
	v_fmac_f32_e32 v58, v59, v56
	v_fma_f32 v52, -v52, v58, v57
	v_div_fmas_f32 v52, v52, v56, v58
	v_div_fixup_f32 v54, v52, v54, 1.0
	v_lshlrev_b32_e32 v52, 16, v53
	v_and_b32_e32 v53, 0xffff0000, v53
	v_mul_f32_e32 v52, 0xbfb8aa3b, v52
	v_mul_f32_e32 v53, 0xbfb8aa3b, v53
	v_exp_f32_e32 v52, v52
	v_exp_f32_e32 v53, v53
	v_pk_mul_f32 v[34:35], v[34:35], v[54:55]
	v_pk_add_f32 v[52:53], v[52:53], 1.0 op_sel_hi:[1,0]
	s_nop 0
	v_div_scale_f32 v54, s[2:3], v53, v53, 1.0
	v_rcp_f32_e32 v55, v54
	v_cvt_pk_bf16_f32 v34, v34, v35
	v_fma_f32 v56, -v54, v55, 1.0
	v_fmac_f32_e32 v55, v56, v55
	v_div_scale_f32 v56, vcc, 1.0, v53, 1.0
	v_mul_f32_e32 v57, v56, v55
	v_fma_f32 v58, -v54, v57, v56
	v_fmac_f32_e32 v57, v58, v55
	v_fma_f32 v54, -v54, v57, v56
	v_div_fmas_f32 v54, v54, v55, v57
	v_div_fixup_f32 v53, v54, v53, 1.0
	v_div_scale_f32 v54, s[2:3], v52, v52, 1.0
	v_rcp_f32_e32 v55, v54
	s_nop 0
	v_fma_f32 v56, -v54, v55, 1.0
	v_fmac_f32_e32 v55, v56, v55
	v_div_scale_f32 v56, vcc, 1.0, v52, 1.0
	v_mul_f32_e32 v57, v56, v55
	v_fma_f32 v58, -v54, v57, v56
	v_fmac_f32_e32 v57, v58, v55
	v_fma_f32 v54, -v54, v57, v56
	v_div_fmas_f32 v54, v54, v55, v57
	v_div_fixup_f32 v52, v54, v52, 1.0
	v_pk_mul_f32 v[36:37], v[36:37], v[52:53]
	s_nop 0
	v_cvt_pk_bf16_f32 v35, v36, v37
	global_store_dwordx2 v[50:51], v[34:35], off offset:64
	v_or_b32_e32 v34, 0x50, v0
	v_mov_b32_e32 v35, v1
	v_lshl_add_u64 v[34:35], v[68:69], 0, v[34:35]
	v_mov_b32_e32 v34, v100
	v_mov_b32_e32 v35, v101
	v_lshlrev_b32_e32 v36, 16, v34
	v_and_b32_e32 v34, 0xffff0000, v34
	v_mul_f32_e32 v36, 0xbfb8aa3b, v36
	v_mul_f32_e32 v34, 0xbfb8aa3b, v34
	v_exp_f32_e32 v36, v36
	v_exp_f32_e32 v37, v34
	s_nop 0
	v_pk_add_f32 v[36:37], v[36:37], 1.0 op_sel_hi:[1,0]
	s_nop 0
	v_div_scale_f32 v34, s[2:3], v37, v37, 1.0
	v_rcp_f32_e32 v52, v34
	s_nop 0
	v_fma_f32 v53, -v34, v52, 1.0
	v_fmac_f32_e32 v52, v53, v52
	v_div_scale_f32 v53, vcc, 1.0, v37, 1.0
	v_mul_f32_e32 v54, v53, v52
	v_fma_f32 v55, -v34, v54, v53
	v_fmac_f32_e32 v54, v55, v52
	v_fma_f32 v34, -v34, v54, v53
	v_div_fmas_f32 v34, v34, v52, v54
	v_div_fixup_f32 v37, v34, v37, 1.0
	v_div_scale_f32 v34, s[2:3], v36, v36, 1.0
	v_rcp_f32_e32 v52, v34
	s_nop 0
	v_fma_f32 v53, -v34, v52, 1.0
	v_fmac_f32_e32 v52, v53, v52
	v_div_scale_f32 v53, vcc, 1.0, v36, 1.0
	v_mul_f32_e32 v54, v53, v52
	v_fma_f32 v55, -v34, v54, v53
	v_fmac_f32_e32 v54, v55, v52
	v_fma_f32 v34, -v34, v54, v53
	v_div_fmas_f32 v34, v34, v52, v54
	v_div_fixup_f32 v36, v34, v36, 1.0
	v_lshlrev_b32_e32 v34, 16, v35
	v_and_b32_e32 v35, 0xffff0000, v35
	v_mul_f32_e32 v34, 0xbfb8aa3b, v34
	v_mul_f32_e32 v35, 0xbfb8aa3b, v35
	v_exp_f32_e32 v34, v34
	v_exp_f32_e32 v35, v35
	v_pk_mul_f32 v[36:37], v[38:39], v[36:37]
	v_pk_mul_f32 v[38:39], v[40:41], v[66:67] op_sel_hi:[1,0]
	v_cvt_pk_bf16_f32 v36, v36, v37
	v_pk_add_f32 v[34:35], v[34:35], 1.0 op_sel_hi:[1,0]
	s_nop 0
	v_div_scale_f32 v40, s[2:3], v35, v35, 1.0
	v_rcp_f32_e32 v41, v40
	s_nop 0
	v_fma_f32 v52, -v40, v41, 1.0
	v_fmac_f32_e32 v41, v52, v41
	v_div_scale_f32 v52, vcc, 1.0, v35, 1.0
	v_mul_f32_e32 v53, v52, v41
	v_fma_f32 v54, -v40, v53, v52
	v_fmac_f32_e32 v53, v54, v41
	v_fma_f32 v40, -v40, v53, v52
	v_div_fmas_f32 v40, v40, v41, v53
	v_div_fixup_f32 v35, v40, v35, 1.0
	v_div_scale_f32 v40, s[2:3], v34, v34, 1.0
	v_rcp_f32_e32 v41, v40
	s_nop 0
	v_fma_f32 v52, -v40, v41, 1.0
	v_fmac_f32_e32 v41, v52, v41
	v_div_scale_f32 v52, vcc, 1.0, v34, 1.0
	v_mul_f32_e32 v53, v52, v41
	v_fma_f32 v54, -v40, v53, v52
	v_fmac_f32_e32 v53, v54, v41
	v_fma_f32 v40, -v40, v53, v52
	v_div_fmas_f32 v40, v40, v41, v53
	v_div_fixup_f32 v34, v40, v34, 1.0
	v_pk_mul_f32 v[34:35], v[38:39], v[34:35]
	v_pk_mul_f32 v[38:39], v[42:43], v[66:67] op_sel_hi:[1,0]
	v_cvt_pk_bf16_f32 v37, v34, v35
	v_or_b32_e32 v34, 0x60, v0
	v_mov_b32_e32 v35, v1
	v_lshl_add_u64 v[34:35], v[68:69], 0, v[34:35]
; DI unsigned pk2(float lo, float hi) { f32x2_t v = {lo, hi}; bf16x2_t b = __builtin_convertvector(v, bf16x2_t); return __builtin_bit_cast(unsigned, b); }
; DI float bflo(unsigned w) { return __uint_as_float(w << 16); }
; DI float bfhi(unsigned w) { return __uint_as_float(w & 0xffff0000u); }
; DI float sigmoidf_(float x) { return 1.f / (1.f + __expf(-x)); }
; template <int DQK, bool FOX>
; DI void attn_unit(const bf16_t* P, int pitch, int b, int qb, int qcol, int kcol, int vcol, bf16_t* Out, int opitch, int ocol, int gcol, const float* cum, lptr lds) {
;     ...
;     for (int d = 0; d < 4; ++d)
; #pragma unroll
;         for (int g = 0; g < 4; ++g) {
;             const int dv = 32 * d + 8 * g + 4 * h;
;             float v[4]; for (int e = 0; e < 4; ++e) v[e] = O[d][4 * g + e] * inv;
;             if (FOX) { const u32x2 gw = *(const u32x2*)(P + tok * pitch + gcol + dv);
;                 v[0] *= sigmoidf_(bflo(gw.x)); v[1] *= sigmoidf_(bfhi(gw.x)); v[2] *= sigmoidf_(bflo(gw.y)); v[3] *= sigmoidf_(bfhi(gw.y)); }
;             u32x2 o; o.x = pk2(v[0], v[1]); o.y = pk2(v[2], v[3]);
;             *(u32x2*)(Out + tok * opitch + ocol + dv) = o;
	v_mov_b32_e32 v34, v102
	v_mov_b32_e32 v35, v103
	s_nop 0
	global_store_dwordx2 v[50:51], v[36:37], off offset:80
	v_lshlrev_b32_e32 v36, 16, v34
	v_and_b32_e32 v34, 0xffff0000, v34
	v_mul_f32_e32 v36, 0xbfb8aa3b, v36
	v_mul_f32_e32 v34, 0xbfb8aa3b, v34
	v_exp_f32_e32 v36, v36
	v_exp_f32_e32 v37, v34
	s_nop 0
	v_pk_add_f32 v[36:37], v[36:37], 1.0 op_sel_hi:[1,0]
	s_nop 0
	v_div_scale_f32 v34, s[2:3], v37, v37, 1.0
	v_rcp_f32_e32 v40, v34
	s_nop 0
	v_fma_f32 v41, -v34, v40, 1.0
	v_fmac_f32_e32 v40, v41, v40
	v_div_scale_f32 v41, vcc, 1.0, v37, 1.0
	v_mul_f32_e32 v42, v41, v40
	v_fma_f32 v43, -v34, v42, v41
	v_fmac_f32_e32 v42, v43, v40
	v_fma_f32 v34, -v34, v42, v41
	v_div_fmas_f32 v34, v34, v40, v42
	v_div_fixup_f32 v37, v34, v37, 1.0
	v_div_scale_f32 v34, s[2:3], v36, v36, 1.0
	v_rcp_f32_e32 v40, v34
	s_nop 0
	v_fma_f32 v41, -v34, v40, 1.0
	v_fmac_f32_e32 v40, v41, v40
	v_div_scale_f32 v41, vcc, 1.0, v36, 1.0
	v_mul_f32_e32 v42, v41, v40
	v_fma_f32 v43, -v34, v42, v41
	v_fmac_f32_e32 v42, v43, v40
	v_fma_f32 v34, -v34, v42, v41
	v_div_fmas_f32 v34, v34, v40, v42
	v_div_fixup_f32 v36, v34, v36, 1.0
	v_lshlrev_b32_e32 v34, 16, v35
	v_and_b32_e32 v35, 0xffff0000, v35
	v_mul_f32_e32 v34, 0xbfb8aa3b, v34
	v_mul_f32_e32 v35, 0xbfb8aa3b, v35
	v_exp_f32_e32 v34, v34
	v_exp_f32_e32 v35, v35
	v_pk_mul_f32 v[36:37], v[38:39], v[36:37]
	v_pk_mul_f32 v[38:39], v[44:45], v[66:67] op_sel_hi:[1,0]
	v_cvt_pk_bf16_f32 v36, v36, v37
	v_pk_add_f32 v[34:35], v[34:35], 1.0 op_sel_hi:[1,0]
	s_nop 0
	v_div_scale_f32 v40, s[2:3], v35, v35, 1.0
	v_rcp_f32_e32 v41, v40
	s_nop 0
	v_fma_f32 v42, -v40, v41, 1.0
	v_fmac_f32_e32 v41, v42, v41
	v_div_scale_f32 v42, vcc, 1.0, v35, 1.0
	v_mul_f32_e32 v43, v42, v41
	v_fma_f32 v44, -v40, v43, v42
	v_fmac_f32_e32 v43, v44, v41
	v_fma_f32 v40, -v40, v43, v42
	v_div_fmas_f32 v40, v40, v41, v43
	v_div_fixup_f32 v35, v40, v35, 1.0
	v_div_scale_f32 v40, s[2:3], v34, v34, 1.0
	v_rcp_f32_e32 v41, v40
	s_nop 0
	v_fma_f32 v42, -v40, v41, 1.0
	v_fmac_f32_e32 v41, v42, v41
	v_div_scale_f32 v42, vcc, 1.0, v34, 1.0
	v_mul_f32_e32 v43, v42, v41
	v_fma_f32 v44, -v40, v43, v42
	v_fmac_f32_e32 v43, v44, v41
	v_fma_f32 v40, -v40, v43, v42
	v_div_fmas_f32 v40, v40, v41, v43
	v_div_fixup_f32 v34, v40, v34, 1.0
	v_pk_mul_f32 v[34:35], v[38:39], v[34:35]
	v_pk_mul_f32 v[38:39], v[46:47], v[66:67] op_sel_hi:[1,0]
	v_cvt_pk_bf16_f32 v37, v34, v35
	v_or_b32_e32 v34, 0x70, v0
	v_mov_b32_e32 v35, v1
	v_lshl_add_u64 v[34:35], v[68:69], 0, v[34:35]
	v_mov_b32_e32 v34, v104
	v_mov_b32_e32 v35, v105
	s_nop 0
	global_store_dwordx2 v[50:51], v[36:37], off offset:96
	v_lshlrev_b32_e32 v36, 16, v34
	v_and_b32_e32 v34, 0xffff0000, v34
	v_mul_f32_e32 v36, 0xbfb8aa3b, v36
	v_mul_f32_e32 v34, 0xbfb8aa3b, v34
	v_exp_f32_e32 v36, v36
	v_exp_f32_e32 v37, v34
	s_nop 0
	v_pk_add_f32 v[36:37], v[36:37], 1.0 op_sel_hi:[1,0]
	s_nop 0
	v_div_scale_f32 v34, s[2:3], v37, v37, 1.0
	v_rcp_f32_e32 v40, v34
	s_nop 0
	v_fma_f32 v41, -v34, v40, 1.0
	v_fmac_f32_e32 v40, v41, v40
	v_div_scale_f32 v41, vcc, 1.0, v37, 1.0
	v_mul_f32_e32 v42, v41, v40
	v_fma_f32 v43, -v34, v42, v41
	v_fmac_f32_e32 v42, v43, v40
	v_fma_f32 v34, -v34, v42, v41
	v_div_fmas_f32 v34, v34, v40, v42
	v_div_fixup_f32 v37, v34, v37, 1.0
	v_div_scale_f32 v34, s[2:3], v36, v36, 1.0
	v_rcp_f32_e32 v40, v34
	s_nop 0
	v_fma_f32 v41, -v34, v40, 1.0
	v_fmac_f32_e32 v40, v41, v40
	v_div_scale_f32 v41, vcc, 1.0, v36, 1.0
	v_mul_f32_e32 v42, v41, v40
	v_fma_f32 v43, -v34, v42, v41
	v_fmac_f32_e32 v42, v43, v40
	v_fma_f32 v34, -v34, v42, v41
	v_div_fmas_f32 v34, v34, v40, v42
	v_div_fixup_f32 v36, v34, v36, 1.0
	v_lshlrev_b32_e32 v34, 16, v35
	v_and_b32_e32 v35, 0xffff0000, v35
	v_mul_f32_e32 v34, 0xbfb8aa3b, v34
	v_mul_f32_e32 v35, 0xbfb8aa3b, v35
	v_exp_f32_e32 v34, v34
	v_exp_f32_e32 v35, v35
	v_pk_mul_f32 v[36:37], v[38:39], v[36:37]
	v_pk_mul_f32 v[38:39], v[48:49], v[66:67] op_sel_hi:[1,0]
	v_cvt_pk_bf16_f32 v36, v36, v37
	v_pk_add_f32 v[34:35], v[34:35], 1.0 op_sel_hi:[1,0]
	s_nop 0
	v_div_scale_f32 v40, s[2:3], v35, v35, 1.0
	v_rcp_f32_e32 v41, v40
	s_nop 0
	v_fma_f32 v42, -v40, v41, 1.0
	v_fmac_f32_e32 v41, v42, v41
	v_div_scale_f32 v42, vcc, 1.0, v35, 1.0
	v_mul_f32_e32 v43, v42, v41
	v_fma_f32 v44, -v40, v43, v42
	v_fmac_f32_e32 v43, v44, v41
	v_fma_f32 v40, -v40, v43, v42
	v_div_fmas_f32 v40, v40, v41, v43
	v_div_fixup_f32 v35, v40, v35, 1.0
	v_div_scale_f32 v40, s[2:3], v34, v34, 1.0
	v_rcp_f32_e32 v41, v40
	s_nop 0
	v_fma_f32 v42, -v40, v41, 1.0
	v_fmac_f32_e32 v41, v42, v41
	v_div_scale_f32 v42, vcc, 1.0, v34, 1.0
	v_mul_f32_e32 v43, v42, v41
	v_fma_f32 v44, -v40, v43, v42
	v_fmac_f32_e32 v43, v44, v41
	v_fma_f32 v40, -v40, v43, v42
	v_div_fmas_f32 v40, v40, v41, v43
	v_div_fixup_f32 v34, v40, v34, 1.0
	v_pk_mul_f32 v[34:35], v[38:39], v[34:35]
	s_nop 0
	v_cvt_pk_bf16_f32 v37, v34, v35
	v_or_b32_e32 v34, 0x80, v0
	v_mov_b32_e32 v35, v1
	v_lshl_add_u64 v[34:35], v[68:69], 0, v[34:35]
	v_mov_b32_e32 v34, v106
	v_mov_b32_e32 v35, v107
	s_nop 0
	global_store_dwordx2 v[50:51], v[36:37], off offset:112
	v_lshlrev_b32_e32 v36, 16, v34
	v_and_b32_e32 v34, 0xffff0000, v34
	v_mul_f32_e32 v36, 0xbfb8aa3b, v36
	v_mul_f32_e32 v34, 0xbfb8aa3b, v34
	v_exp_f32_e32 v36, v36
	v_exp_f32_e32 v37, v34
	s_nop 0
	v_pk_add_f32 v[36:37], v[36:37], 1.0 op_sel_hi:[1,0]
	s_nop 0
	v_div_scale_f32 v34, s[2:3], v37, v37, 1.0
	v_rcp_f32_e32 v38, v34
	s_nop 0
	v_fma_f32 v39, -v34, v38, 1.0
	v_fmac_f32_e32 v38, v39, v38
	v_div_scale_f32 v39, vcc, 1.0, v37, 1.0
	v_mul_f32_e32 v40, v39, v38
	v_fma_f32 v41, -v34, v40, v39
	v_fmac_f32_e32 v40, v41, v38
	v_fma_f32 v34, -v34, v40, v39
	v_div_fmas_f32 v34, v34, v38, v40
	v_div_fixup_f32 v37, v34, v37, 1.0
; DI unsigned pk2(float lo, float hi) { f32x2_t v = {lo, hi}; bf16x2_t b = __builtin_convertvector(v, bf16x2_t); return __builtin_bit_cast(unsigned, b); }
; DI float bflo(unsigned w) { return __uint_as_float(w << 16); }
; DI float bfhi(unsigned w) { return __uint_as_float(w & 0xffff0000u); }
; DI float sigmoidf_(float x) { return 1.f / (1.f + __expf(-x)); }
; template <int DQK, bool FOX>
; DI void attn_unit(const bf16_t* P, int pitch, int b, int qb, int qcol, int kcol, int vcol, bf16_t* Out, int opitch, int ocol, int gcol, const float* cum, lptr lds) {
;     ...
;     for (int d = 0; d < 4; ++d)
; #pragma unroll
;         for (int g = 0; g < 4; ++g) {
;             const int dv = 32 * d + 8 * g + 4 * h;
;             float v[4]; for (int e = 0; e < 4; ++e) v[e] = O[d][4 * g + e] * inv;
;             if (FOX) { const u32x2 gw = *(const u32x2*)(P + tok * pitch + gcol + dv);
;                 v[0] *= sigmoidf_(bflo(gw.x)); v[1] *= sigmoidf_(bfhi(gw.x)); v[2] *= sigmoidf_(bflo(gw.y)); v[3] *= sigmoidf_(bfhi(gw.y)); }
;             u32x2 o; o.x = pk2(v[0], v[1]); o.y = pk2(v[2], v[3]);
;             *(u32x2*)(Out + tok * opitch + ocol + dv) = o;
	v_div_scale_f32 v34, s[2:3], v36, v36, 1.0
	v_rcp_f32_e32 v38, v34
	s_nop 0
	v_fma_f32 v39, -v34, v38, 1.0
	v_fmac_f32_e32 v38, v39, v38
	v_div_scale_f32 v39, vcc, 1.0, v36, 1.0
	v_mul_f32_e32 v40, v39, v38
	v_fma_f32 v41, -v34, v40, v39
	v_fmac_f32_e32 v40, v41, v38
	v_fma_f32 v34, -v34, v40, v39
	v_div_fmas_f32 v34, v34, v38, v40
	v_div_fixup_f32 v36, v34, v36, 1.0
	v_lshlrev_b32_e32 v34, 16, v35
	v_and_b32_e32 v35, 0xffff0000, v35
	v_mul_f32_e32 v34, 0xbfb8aa3b, v34
	v_mul_f32_e32 v35, 0xbfb8aa3b, v35
	v_exp_f32_e32 v34, v34
	v_exp_f32_e32 v35, v35
	v_pk_mul_f32 v[18:19], v[18:19], v[36:37]
	v_pk_add_f32 v[34:35], v[34:35], 1.0 op_sel_hi:[1,0]
	s_nop 0
	v_div_scale_f32 v36, s[2:3], v35, v35, 1.0
	v_rcp_f32_e32 v37, v36
	v_cvt_pk_bf16_f32 v18, v18, v19
	v_fma_f32 v38, -v36, v37, 1.0
	v_fmac_f32_e32 v37, v38, v37
	v_div_scale_f32 v38, vcc, 1.0, v35, 1.0
	v_mul_f32_e32 v39, v38, v37
	v_fma_f32 v40, -v36, v39, v38
	v_fmac_f32_e32 v39, v40, v37
	v_fma_f32 v36, -v36, v39, v38
	v_div_fmas_f32 v36, v36, v37, v39
	v_div_fixup_f32 v35, v36, v35, 1.0
	v_div_scale_f32 v36, s[2:3], v34, v34, 1.0
	v_rcp_f32_e32 v37, v36
	s_nop 0
	v_fma_f32 v38, -v36, v37, 1.0
	v_fmac_f32_e32 v37, v38, v37
	v_div_scale_f32 v38, vcc, 1.0, v34, 1.0
	v_mul_f32_e32 v39, v38, v37
	v_fma_f32 v40, -v36, v39, v38
	v_fmac_f32_e32 v39, v40, v37
	v_fma_f32 v36, -v36, v39, v38
	v_div_fmas_f32 v36, v36, v37, v39
	v_div_fixup_f32 v34, v36, v34, 1.0
	v_pk_mul_f32 v[20:21], v[20:21], v[34:35]
	s_nop 0
	v_cvt_pk_bf16_f32 v19, v20, v21
	global_store_dwordx2 v[50:51], v[18:19], off offset:128
	v_or_b32_e32 v18, 0x90, v0
	v_mov_b32_e32 v19, v1
	v_lshl_add_u64 v[18:19], v[68:69], 0, v[18:19]
	v_mov_b32_e32 v18, v108
	v_mov_b32_e32 v19, v109
	v_lshlrev_b32_e32 v20, 16, v18
	v_and_b32_e32 v18, 0xffff0000, v18
	v_mul_f32_e32 v20, 0xbfb8aa3b, v20
	v_mul_f32_e32 v18, 0xbfb8aa3b, v18
	v_exp_f32_e32 v20, v20
	v_exp_f32_e32 v21, v18
	s_nop 0
	v_pk_add_f32 v[20:21], v[20:21], 1.0 op_sel_hi:[1,0]
	s_nop 0
	v_div_scale_f32 v18, s[2:3], v21, v21, 1.0
	v_rcp_f32_e32 v34, v18
	s_nop 0
	v_fma_f32 v35, -v18, v34, 1.0
	v_fmac_f32_e32 v34, v35, v34
	v_div_scale_f32 v35, vcc, 1.0, v21, 1.0
	v_mul_f32_e32 v36, v35, v34
	v_fma_f32 v37, -v18, v36, v35
	v_fmac_f32_e32 v36, v37, v34
	v_fma_f32 v18, -v18, v36, v35
	v_div_fmas_f32 v18, v18, v34, v36
	v_div_fixup_f32 v21, v18, v21, 1.0
	v_div_scale_f32 v18, s[2:3], v20, v20, 1.0
	v_rcp_f32_e32 v34, v18
	s_nop 0
	v_fma_f32 v35, -v18, v34, 1.0
	v_fmac_f32_e32 v34, v35, v34
	v_div_scale_f32 v35, vcc, 1.0, v20, 1.0
	v_mul_f32_e32 v36, v35, v34
	v_fma_f32 v37, -v18, v36, v35
	v_fmac_f32_e32 v36, v37, v34
	v_fma_f32 v18, -v18, v36, v35
	v_div_fmas_f32 v18, v18, v34, v36
	v_div_fixup_f32 v20, v18, v20, 1.0
	v_lshlrev_b32_e32 v18, 16, v19
	v_and_b32_e32 v19, 0xffff0000, v19
	v_mul_f32_e32 v18, 0xbfb8aa3b, v18
	v_mul_f32_e32 v19, 0xbfb8aa3b, v19
	v_exp_f32_e32 v18, v18
	v_exp_f32_e32 v19, v19
	v_pk_mul_f32 v[20:21], v[22:23], v[20:21]
	v_pk_mul_f32 v[22:23], v[24:25], v[66:67] op_sel_hi:[1,0]
	v_cvt_pk_bf16_f32 v20, v20, v21
	v_pk_add_f32 v[18:19], v[18:19], 1.0 op_sel_hi:[1,0]
	s_nop 0
	v_div_scale_f32 v24, s[2:3], v19, v19, 1.0
	v_rcp_f32_e32 v25, v24
	s_nop 0
	v_fma_f32 v34, -v24, v25, 1.0
	v_fmac_f32_e32 v25, v34, v25
	v_div_scale_f32 v34, vcc, 1.0, v19, 1.0
	v_mul_f32_e32 v35, v34, v25
	v_fma_f32 v36, -v24, v35, v34
	v_fmac_f32_e32 v35, v36, v25
	v_fma_f32 v24, -v24, v35, v34
	v_div_fmas_f32 v24, v24, v25, v35
	v_div_fixup_f32 v19, v24, v19, 1.0
	v_div_scale_f32 v24, s[2:3], v18, v18, 1.0
	v_rcp_f32_e32 v25, v24
	s_nop 0
	v_fma_f32 v34, -v24, v25, 1.0
	v_fmac_f32_e32 v25, v34, v25
	v_div_scale_f32 v34, vcc, 1.0, v18, 1.0
	v_mul_f32_e32 v35, v34, v25
	v_fma_f32 v36, -v24, v35, v34
	v_fmac_f32_e32 v35, v36, v25
	v_fma_f32 v24, -v24, v35, v34
	v_div_fmas_f32 v24, v24, v25, v35
	v_div_fixup_f32 v18, v24, v18, 1.0
	v_pk_mul_f32 v[18:19], v[22:23], v[18:19]
	v_pk_mul_f32 v[22:23], v[26:27], v[66:67] op_sel_hi:[1,0]
	v_cvt_pk_bf16_f32 v21, v18, v19
	v_or_b32_e32 v18, 0xa0, v0
	v_mov_b32_e32 v19, v1
	v_lshl_add_u64 v[18:19], v[68:69], 0, v[18:19]
	v_mov_b32_e32 v18, v110
	v_mov_b32_e32 v19, v111
	s_nop 0
	global_store_dwordx2 v[50:51], v[20:21], off offset:144
	v_lshlrev_b32_e32 v20, 16, v18
	v_and_b32_e32 v18, 0xffff0000, v18
	v_mul_f32_e32 v20, 0xbfb8aa3b, v20
	v_mul_f32_e32 v18, 0xbfb8aa3b, v18
	v_exp_f32_e32 v20, v20
	v_exp_f32_e32 v21, v18
	s_nop 0
	v_pk_add_f32 v[20:21], v[20:21], 1.0 op_sel_hi:[1,0]
	s_nop 0
	v_div_scale_f32 v18, s[2:3], v21, v21, 1.0
	v_rcp_f32_e32 v24, v18
	s_nop 0
	v_fma_f32 v25, -v18, v24, 1.0
	v_fmac_f32_e32 v24, v25, v24
	v_div_scale_f32 v25, vcc, 1.0, v21, 1.0
	v_mul_f32_e32 v26, v25, v24
	v_fma_f32 v27, -v18, v26, v25
	v_fmac_f32_e32 v26, v27, v24
	v_fma_f32 v18, -v18, v26, v25
	v_div_fmas_f32 v18, v18, v24, v26
	v_div_fixup_f32 v21, v18, v21, 1.0
	v_div_scale_f32 v18, s[2:3], v20, v20, 1.0
	v_rcp_f32_e32 v24, v18
	s_nop 0
	v_fma_f32 v25, -v18, v24, 1.0
	v_fmac_f32_e32 v24, v25, v24
	v_div_scale_f32 v25, vcc, 1.0, v20, 1.0
	v_mul_f32_e32 v26, v25, v24
	v_fma_f32 v27, -v18, v26, v25
	v_fmac_f32_e32 v26, v27, v24
	v_fma_f32 v18, -v18, v26, v25
	v_div_fmas_f32 v18, v18, v24, v26
	v_div_fixup_f32 v20, v18, v20, 1.0
	v_lshlrev_b32_e32 v18, 16, v19
	v_and_b32_e32 v19, 0xffff0000, v19
	v_mul_f32_e32 v18, 0xbfb8aa3b, v18
	v_mul_f32_e32 v19, 0xbfb8aa3b, v19
	v_exp_f32_e32 v18, v18
	v_exp_f32_e32 v19, v19
	v_pk_mul_f32 v[20:21], v[22:23], v[20:21]
	v_pk_mul_f32 v[22:23], v[28:29], v[66:67] op_sel_hi:[1,0]
	v_cvt_pk_bf16_f32 v20, v20, v21
	v_pk_add_f32 v[18:19], v[18:19], 1.0 op_sel_hi:[1,0]
	s_nop 0
	v_div_scale_f32 v24, s[2:3], v19, v19, 1.0
; DI unsigned pk2(float lo, float hi) { f32x2_t v = {lo, hi}; bf16x2_t b = __builtin_convertvector(v, bf16x2_t); return __builtin_bit_cast(unsigned, b); }
; DI float bflo(unsigned w) { return __uint_as_float(w << 16); }
; DI float bfhi(unsigned w) { return __uint_as_float(w & 0xffff0000u); }
; DI float sigmoidf_(float x) { return 1.f / (1.f + __expf(-x)); }
; template <int DQK, bool FOX>
; DI void attn_unit(const bf16_t* P, int pitch, int b, int qb, int qcol, int kcol, int vcol, bf16_t* Out, int opitch, int ocol, int gcol, const float* cum, lptr lds) {
;     ...
;     for (int d = 0; d < 4; ++d)
; #pragma unroll
;         for (int g = 0; g < 4; ++g) {
;             const int dv = 32 * d + 8 * g + 4 * h;
;             float v[4]; for (int e = 0; e < 4; ++e) v[e] = O[d][4 * g + e] * inv;
;             if (FOX) { const u32x2 gw = *(const u32x2*)(P + tok * pitch + gcol + dv);
;                 v[0] *= sigmoidf_(bflo(gw.x)); v[1] *= sigmoidf_(bfhi(gw.x)); v[2] *= sigmoidf_(bflo(gw.y)); v[3] *= sigmoidf_(bfhi(gw.y)); }
;             u32x2 o; o.x = pk2(v[0], v[1]); o.y = pk2(v[2], v[3]);
;             *(u32x2*)(Out + tok * opitch + ocol + dv) = o;
	v_rcp_f32_e32 v25, v24
	s_nop 0
	v_fma_f32 v26, -v24, v25, 1.0
	v_fmac_f32_e32 v25, v26, v25
	v_div_scale_f32 v26, vcc, 1.0, v19, 1.0
	v_mul_f32_e32 v27, v26, v25
	v_fma_f32 v28, -v24, v27, v26
	v_fmac_f32_e32 v27, v28, v25
	v_fma_f32 v24, -v24, v27, v26
	v_div_fmas_f32 v24, v24, v25, v27
	v_div_fixup_f32 v19, v24, v19, 1.0
	v_div_scale_f32 v24, s[2:3], v18, v18, 1.0
	v_rcp_f32_e32 v25, v24
	s_nop 0
	v_fma_f32 v26, -v24, v25, 1.0
	v_fmac_f32_e32 v25, v26, v25
	v_div_scale_f32 v26, vcc, 1.0, v18, 1.0
	v_mul_f32_e32 v27, v26, v25
	v_fma_f32 v28, -v24, v27, v26
	v_fmac_f32_e32 v27, v28, v25
	v_fma_f32 v24, -v24, v27, v26
	v_div_fmas_f32 v24, v24, v25, v27
	v_div_fixup_f32 v18, v24, v18, 1.0
	v_pk_mul_f32 v[18:19], v[22:23], v[18:19]
	v_pk_mul_f32 v[22:23], v[30:31], v[66:67] op_sel_hi:[1,0]
	v_cvt_pk_bf16_f32 v21, v18, v19
	v_or_b32_e32 v18, 0xb0, v0
	v_mov_b32_e32 v19, v1
	v_lshl_add_u64 v[18:19], v[68:69], 0, v[18:19]
	v_mov_b32_e32 v18, v112
	v_mov_b32_e32 v19, v113
	s_nop 0
	global_store_dwordx2 v[50:51], v[20:21], off offset:160
	v_lshlrev_b32_e32 v20, 16, v18
	v_and_b32_e32 v18, 0xffff0000, v18
	v_mul_f32_e32 v20, 0xbfb8aa3b, v20
	v_mul_f32_e32 v18, 0xbfb8aa3b, v18
	v_exp_f32_e32 v20, v20
	v_exp_f32_e32 v21, v18
	s_nop 0
	v_pk_add_f32 v[20:21], v[20:21], 1.0 op_sel_hi:[1,0]
	s_nop 0
	v_div_scale_f32 v18, s[2:3], v21, v21, 1.0
	v_rcp_f32_e32 v24, v18
	s_nop 0
	v_fma_f32 v25, -v18, v24, 1.0
	v_fmac_f32_e32 v24, v25, v24
	v_div_scale_f32 v25, vcc, 1.0, v21, 1.0
	v_mul_f32_e32 v26, v25, v24
	v_fma_f32 v27, -v18, v26, v25
	v_fmac_f32_e32 v26, v27, v24
	v_fma_f32 v18, -v18, v26, v25
	v_div_fmas_f32 v18, v18, v24, v26
	v_div_fixup_f32 v21, v18, v21, 1.0
	v_div_scale_f32 v18, s[2:3], v20, v20, 1.0
	v_rcp_f32_e32 v24, v18
	s_nop 0
	v_fma_f32 v25, -v18, v24, 1.0
	v_fmac_f32_e32 v24, v25, v24
	v_div_scale_f32 v25, vcc, 1.0, v20, 1.0
	v_mul_f32_e32 v26, v25, v24
	v_fma_f32 v27, -v18, v26, v25
	v_fmac_f32_e32 v26, v27, v24
	v_fma_f32 v18, -v18, v26, v25
	v_div_fmas_f32 v18, v18, v24, v26
	v_div_fixup_f32 v20, v18, v20, 1.0
	v_lshlrev_b32_e32 v18, 16, v19
	v_and_b32_e32 v19, 0xffff0000, v19
	v_mul_f32_e32 v18, 0xbfb8aa3b, v18
	v_mul_f32_e32 v19, 0xbfb8aa3b, v19
	v_exp_f32_e32 v18, v18
	v_exp_f32_e32 v19, v19
	v_pk_mul_f32 v[20:21], v[22:23], v[20:21]
	v_pk_mul_f32 v[22:23], v[32:33], v[66:67] op_sel_hi:[1,0]
	v_cvt_pk_bf16_f32 v20, v20, v21
	v_pk_add_f32 v[18:19], v[18:19], 1.0 op_sel_hi:[1,0]
	s_nop 0
	v_div_scale_f32 v24, s[2:3], v19, v19, 1.0
	v_rcp_f32_e32 v25, v24
	s_nop 0
	v_fma_f32 v26, -v24, v25, 1.0
	v_fmac_f32_e32 v25, v26, v25
	v_div_scale_f32 v26, vcc, 1.0, v19, 1.0
	v_mul_f32_e32 v27, v26, v25
	v_fma_f32 v28, -v24, v27, v26
	v_fmac_f32_e32 v27, v28, v25
	v_fma_f32 v24, -v24, v27, v26
	v_div_fmas_f32 v24, v24, v25, v27
	v_div_fixup_f32 v19, v24, v19, 1.0
	v_div_scale_f32 v24, s[2:3], v18, v18, 1.0
	v_rcp_f32_e32 v25, v24
	s_nop 0
	v_fma_f32 v26, -v24, v25, 1.0
	v_fmac_f32_e32 v25, v26, v25
	v_div_scale_f32 v26, vcc, 1.0, v18, 1.0
	v_mul_f32_e32 v27, v26, v25
	v_fma_f32 v28, -v24, v27, v26
	v_fmac_f32_e32 v27, v28, v25
	v_fma_f32 v24, -v24, v27, v26
	v_div_fmas_f32 v24, v24, v25, v27
	v_div_fixup_f32 v18, v24, v18, 1.0
	v_pk_mul_f32 v[18:19], v[22:23], v[18:19]
	s_nop 0
	v_cvt_pk_bf16_f32 v21, v18, v19
	v_or_b32_e32 v18, 0xc0, v0
	v_mov_b32_e32 v19, v1
	v_lshl_add_u64 v[18:19], v[68:69], 0, v[18:19]
	v_mov_b32_e32 v18, v114
	v_mov_b32_e32 v19, v115
	s_nop 0
	global_store_dwordx2 v[50:51], v[20:21], off offset:176
	v_lshlrev_b32_e32 v20, 16, v18
	v_and_b32_e32 v18, 0xffff0000, v18
	v_mul_f32_e32 v20, 0xbfb8aa3b, v20
	v_mul_f32_e32 v18, 0xbfb8aa3b, v18
	v_exp_f32_e32 v20, v20
	v_exp_f32_e32 v21, v18
	s_nop 0
	v_pk_add_f32 v[20:21], v[20:21], 1.0 op_sel_hi:[1,0]
	s_nop 0
	v_div_scale_f32 v18, s[2:3], v21, v21, 1.0
	v_rcp_f32_e32 v22, v18
	s_nop 0
	v_fma_f32 v23, -v18, v22, 1.0
	v_fmac_f32_e32 v22, v23, v22
	v_div_scale_f32 v23, vcc, 1.0, v21, 1.0
	v_mul_f32_e32 v24, v23, v22
	v_fma_f32 v25, -v18, v24, v23
	v_fmac_f32_e32 v24, v25, v22
	v_fma_f32 v18, -v18, v24, v23
	v_div_fmas_f32 v18, v18, v22, v24
	v_div_fixup_f32 v21, v18, v21, 1.0
	v_div_scale_f32 v18, s[2:3], v20, v20, 1.0
	v_rcp_f32_e32 v22, v18
	s_nop 0
	v_fma_f32 v23, -v18, v22, 1.0
	v_fmac_f32_e32 v22, v23, v22
	v_div_scale_f32 v23, vcc, 1.0, v20, 1.0
	v_mul_f32_e32 v24, v23, v22
	v_fma_f32 v25, -v18, v24, v23
	v_fmac_f32_e32 v24, v25, v22
	v_fma_f32 v18, -v18, v24, v23
	v_div_fmas_f32 v18, v18, v22, v24
	v_div_fixup_f32 v20, v18, v20, 1.0
	v_lshlrev_b32_e32 v18, 16, v19
	v_and_b32_e32 v19, 0xffff0000, v19
	v_mul_f32_e32 v18, 0xbfb8aa3b, v18
	v_mul_f32_e32 v19, 0xbfb8aa3b, v19
	v_exp_f32_e32 v18, v18
	v_exp_f32_e32 v19, v19
	v_pk_mul_f32 v[2:3], v[2:3], v[20:21]
	v_pk_add_f32 v[18:19], v[18:19], 1.0 op_sel_hi:[1,0]
	s_nop 0
	v_div_scale_f32 v20, s[2:3], v19, v19, 1.0
	v_rcp_f32_e32 v21, v20
	v_cvt_pk_bf16_f32 v2, v2, v3
	v_fma_f32 v22, -v20, v21, 1.0
	v_fmac_f32_e32 v21, v22, v21
	v_div_scale_f32 v22, vcc, 1.0, v19, 1.0
	v_mul_f32_e32 v23, v22, v21
	v_fma_f32 v24, -v20, v23, v22
	v_fmac_f32_e32 v23, v24, v21
	v_fma_f32 v20, -v20, v23, v22
	v_div_fmas_f32 v20, v20, v21, v23
	v_div_fixup_f32 v19, v20, v19, 1.0
	v_div_scale_f32 v20, s[2:3], v18, v18, 1.0
	v_rcp_f32_e32 v21, v20
	s_nop 0
	v_fma_f32 v22, -v20, v21, 1.0
	v_fmac_f32_e32 v21, v22, v21
	v_div_scale_f32 v22, vcc, 1.0, v18, 1.0
	v_mul_f32_e32 v23, v22, v21
	v_fma_f32 v24, -v20, v23, v22
	v_fmac_f32_e32 v23, v24, v21
	v_fma_f32 v20, -v20, v23, v22
	v_div_fmas_f32 v20, v20, v21, v23
	v_div_fixup_f32 v18, v20, v18, 1.0
	v_pk_mul_f32 v[4:5], v[4:5], v[18:19]
	s_nop 0
	v_cvt_pk_bf16_f32 v3, v4, v5
	global_store_dwordx2 v[50:51], v[2:3], off offset:192
; DI unsigned pk2(float lo, float hi) { f32x2_t v = {lo, hi}; bf16x2_t b = __builtin_convertvector(v, bf16x2_t); return __builtin_bit_cast(unsigned, b); }
; DI float bflo(unsigned w) { return __uint_as_float(w << 16); }
; DI float bfhi(unsigned w) { return __uint_as_float(w & 0xffff0000u); }
; DI float sigmoidf_(float x) { return 1.f / (1.f + __expf(-x)); }
; template <int DQK, bool FOX>
; DI void attn_unit(const bf16_t* P, int pitch, int b, int qb, int qcol, int kcol, int vcol, bf16_t* Out, int opitch, int ocol, int gcol, const float* cum, lptr lds) {
;     ...
;     for (int d = 0; d < 4; ++d)
; #pragma unroll
;         for (int g = 0; g < 4; ++g) {
;             const int dv = 32 * d + 8 * g + 4 * h;
;             float v[4]; for (int e = 0; e < 4; ++e) v[e] = O[d][4 * g + e] * inv;
;             if (FOX) { const u32x2 gw = *(const u32x2*)(P + tok * pitch + gcol + dv);
;                 v[0] *= sigmoidf_(bflo(gw.x)); v[1] *= sigmoidf_(bfhi(gw.x)); v[2] *= sigmoidf_(bflo(gw.y)); v[3] *= sigmoidf_(bfhi(gw.y)); }
;             u32x2 o; o.x = pk2(v[0], v[1]); o.y = pk2(v[2], v[3]);
;             *(u32x2*)(Out + tok * opitch + ocol + dv) = o;
;         }
	v_or_b32_e32 v2, 0xd0, v0
	v_mov_b32_e32 v3, v1
	v_lshl_add_u64 v[2:3], v[68:69], 0, v[2:3]
	v_mov_b32_e32 v2, v116
	v_mov_b32_e32 v3, v117
	v_lshlrev_b32_e32 v4, 16, v2
	v_and_b32_e32 v2, 0xffff0000, v2
	v_mul_f32_e32 v4, 0xbfb8aa3b, v4
	v_mul_f32_e32 v2, 0xbfb8aa3b, v2
	v_exp_f32_e32 v4, v4
	v_exp_f32_e32 v5, v2
	s_nop 0
	v_pk_add_f32 v[4:5], v[4:5], 1.0 op_sel_hi:[1,0]
	s_nop 0
	v_div_scale_f32 v2, s[2:3], v5, v5, 1.0
	v_rcp_f32_e32 v18, v2
	s_nop 0
	v_fma_f32 v19, -v2, v18, 1.0
	v_fmac_f32_e32 v18, v19, v18
	v_div_scale_f32 v19, vcc, 1.0, v5, 1.0
	v_mul_f32_e32 v20, v19, v18
	v_fma_f32 v21, -v2, v20, v19
	v_fmac_f32_e32 v20, v21, v18
	v_fma_f32 v2, -v2, v20, v19
	v_div_fmas_f32 v2, v2, v18, v20
	v_div_fixup_f32 v5, v2, v5, 1.0
	v_div_scale_f32 v2, s[2:3], v4, v4, 1.0
	v_rcp_f32_e32 v18, v2
	s_nop 0
	v_fma_f32 v19, -v2, v18, 1.0
	v_fmac_f32_e32 v18, v19, v18
	v_div_scale_f32 v19, vcc, 1.0, v4, 1.0
	v_mul_f32_e32 v20, v19, v18
	v_fma_f32 v21, -v2, v20, v19
	v_fmac_f32_e32 v20, v21, v18
	v_fma_f32 v2, -v2, v20, v19
	v_div_fmas_f32 v2, v2, v18, v20
	v_div_fixup_f32 v4, v2, v4, 1.0
	v_lshlrev_b32_e32 v2, 16, v3
	v_and_b32_e32 v3, 0xffff0000, v3
	v_mul_f32_e32 v2, 0xbfb8aa3b, v2
	v_mul_f32_e32 v3, 0xbfb8aa3b, v3
	v_exp_f32_e32 v2, v2
	v_exp_f32_e32 v3, v3
	v_pk_mul_f32 v[4:5], v[6:7], v[4:5]
	v_pk_mul_f32 v[6:7], v[8:9], v[66:67] op_sel_hi:[1,0]
	v_cvt_pk_bf16_f32 v4, v4, v5
	v_pk_add_f32 v[2:3], v[2:3], 1.0 op_sel_hi:[1,0]
	s_nop 0
	v_div_scale_f32 v8, s[2:3], v3, v3, 1.0
	v_rcp_f32_e32 v9, v8
	s_nop 0
	v_fma_f32 v18, -v8, v9, 1.0
	v_fmac_f32_e32 v9, v18, v9
	v_div_scale_f32 v18, vcc, 1.0, v3, 1.0
	v_mul_f32_e32 v19, v18, v9
	v_fma_f32 v20, -v8, v19, v18
	v_fmac_f32_e32 v19, v20, v9
	v_fma_f32 v8, -v8, v19, v18
	v_div_fmas_f32 v8, v8, v9, v19
	v_div_fixup_f32 v3, v8, v3, 1.0
	v_div_scale_f32 v8, s[2:3], v2, v2, 1.0
	v_rcp_f32_e32 v9, v8
	s_nop 0
	v_fma_f32 v18, -v8, v9, 1.0
	v_fmac_f32_e32 v9, v18, v9
	v_div_scale_f32 v18, vcc, 1.0, v2, 1.0
	v_mul_f32_e32 v19, v18, v9
	v_fma_f32 v20, -v8, v19, v18
	v_fmac_f32_e32 v19, v20, v9
	v_fma_f32 v8, -v8, v19, v18
	v_div_fmas_f32 v8, v8, v9, v19
	v_div_fixup_f32 v2, v8, v2, 1.0
	v_pk_mul_f32 v[2:3], v[6:7], v[2:3]
	v_pk_mul_f32 v[6:7], v[10:11], v[66:67] op_sel_hi:[1,0]
	v_cvt_pk_bf16_f32 v5, v2, v3
	v_or_b32_e32 v2, 0xe0, v0
	v_mov_b32_e32 v3, v1
	v_lshl_add_u64 v[2:3], v[68:69], 0, v[2:3]
	v_mov_b32_e32 v2, v118
	v_mov_b32_e32 v3, v119
	v_or_b32_e32 v0, 0xf0, v0
	global_store_dwordx2 v[50:51], v[4:5], off offset:208
	v_lshlrev_b32_e32 v4, 16, v2
	v_and_b32_e32 v2, 0xffff0000, v2
	v_mul_f32_e32 v4, 0xbfb8aa3b, v4
	v_mul_f32_e32 v2, 0xbfb8aa3b, v2
	v_exp_f32_e32 v4, v4
	v_exp_f32_e32 v5, v2
	s_nop 0
	v_pk_add_f32 v[4:5], v[4:5], 1.0 op_sel_hi:[1,0]
	s_nop 0
	v_div_scale_f32 v2, s[2:3], v5, v5, 1.0
	v_rcp_f32_e32 v8, v2
	s_nop 0
	v_fma_f32 v9, -v2, v8, 1.0
	v_fmac_f32_e32 v8, v9, v8
	v_div_scale_f32 v9, vcc, 1.0, v5, 1.0
	v_mul_f32_e32 v10, v9, v8
	v_fma_f32 v11, -v2, v10, v9
	v_fmac_f32_e32 v10, v11, v8
	v_fma_f32 v2, -v2, v10, v9
	v_div_fmas_f32 v2, v2, v8, v10
	v_div_fixup_f32 v5, v2, v5, 1.0
	v_div_scale_f32 v2, s[2:3], v4, v4, 1.0
	v_rcp_f32_e32 v8, v2
	s_nop 0
	v_fma_f32 v9, -v2, v8, 1.0
	v_fmac_f32_e32 v8, v9, v8
	v_div_scale_f32 v9, vcc, 1.0, v4, 1.0
	v_mul_f32_e32 v10, v9, v8
	v_fma_f32 v11, -v2, v10, v9
	v_fmac_f32_e32 v10, v11, v8
	v_fma_f32 v2, -v2, v10, v9
	v_div_fmas_f32 v2, v2, v8, v10
	v_div_fixup_f32 v4, v2, v4, 1.0
	v_lshlrev_b32_e32 v2, 16, v3
	v_and_b32_e32 v3, 0xffff0000, v3
	v_mul_f32_e32 v2, 0xbfb8aa3b, v2
	v_mul_f32_e32 v3, 0xbfb8aa3b, v3
	v_exp_f32_e32 v2, v2
	v_exp_f32_e32 v3, v3
	v_pk_mul_f32 v[4:5], v[6:7], v[4:5]
	v_pk_mul_f32 v[6:7], v[12:13], v[66:67] op_sel_hi:[1,0]
	v_cvt_pk_bf16_f32 v4, v4, v5
	v_pk_add_f32 v[2:3], v[2:3], 1.0 op_sel_hi:[1,0]
	s_nop 0
	v_div_scale_f32 v8, s[2:3], v3, v3, 1.0
	v_rcp_f32_e32 v9, v8
	s_nop 0
	v_fma_f32 v10, -v8, v9, 1.0
	v_fmac_f32_e32 v9, v10, v9
	v_div_scale_f32 v10, vcc, 1.0, v3, 1.0
	v_mul_f32_e32 v11, v10, v9
	v_fma_f32 v12, -v8, v11, v10
	v_fmac_f32_e32 v11, v12, v9
	v_fma_f32 v8, -v8, v11, v10
	v_div_fmas_f32 v8, v8, v9, v11
	v_div_fixup_f32 v3, v8, v3, 1.0
	v_div_scale_f32 v8, s[2:3], v2, v2, 1.0
	v_rcp_f32_e32 v9, v8
	s_nop 0
	v_fma_f32 v10, -v8, v9, 1.0
	v_fmac_f32_e32 v9, v10, v9
	v_div_scale_f32 v10, vcc, 1.0, v2, 1.0
	v_mul_f32_e32 v11, v10, v9
	v_fma_f32 v12, -v8, v11, v10
	v_fmac_f32_e32 v11, v12, v9
	v_fma_f32 v8, -v8, v11, v10
	v_div_fmas_f32 v8, v8, v9, v11
	v_div_fixup_f32 v2, v8, v2, 1.0
	v_pk_mul_f32 v[2:3], v[6:7], v[2:3]
	v_pk_mul_f32 v[6:7], v[14:15], v[66:67] op_sel_hi:[1,0]
	v_cvt_pk_bf16_f32 v5, v2, v3
	v_lshl_add_u64 v[2:3], v[68:69], 0, v[0:1]
	v_mov_b32_e32 v2, v120
	v_mov_b32_e32 v3, v121
	v_lshlrev_b32_e32 v0, 16, v2
	v_mul_f32_e32 v0, 0xbfb8aa3b, v0
	global_store_dwordx2 v[50:51], v[4:5], off offset:224
	v_exp_f32_e32 v4, v0
	v_and_b32_e32 v0, 0xffff0000, v2
	v_mul_f32_e32 v0, 0xbfb8aa3b, v0
	v_exp_f32_e32 v5, v0
	s_nop 0
	v_pk_add_f32 v[4:5], v[4:5], 1.0 op_sel_hi:[1,0]
	s_nop 0
	v_div_scale_f32 v0, s[2:3], v5, v5, 1.0
	v_rcp_f32_e32 v2, v0
	s_nop 0
	v_fma_f32 v8, -v0, v2, 1.0
	v_fmac_f32_e32 v2, v8, v2
	v_div_scale_f32 v8, vcc, 1.0, v5, 1.0
	v_mul_f32_e32 v9, v8, v2
	v_fma_f32 v10, -v0, v9, v8
	v_fmac_f32_e32 v9, v10, v2
	v_fma_f32 v0, -v0, v9, v8
	v_div_fmas_f32 v0, v0, v2, v9
	v_div_fixup_f32 v5, v0, v5, 1.0
	v_div_scale_f32 v0, s[2:3], v4, v4, 1.0
	v_rcp_f32_e32 v2, v0
	s_nop 0
	v_fma_f32 v8, -v0, v2, 1.0
	v_fmac_f32_e32 v2, v8, v2
	v_div_scale_f32 v8, vcc, 1.0, v4, 1.0
	v_mul_f32_e32 v9, v8, v2
	v_fma_f32 v10, -v0, v9, v8
	v_fmac_f32_e32 v9, v10, v2
	v_fma_f32 v0, -v0, v9, v8
	v_div_fmas_f32 v0, v0, v2, v9
	v_div_fixup_f32 v4, v0, v4, 1.0
	v_lshlrev_b32_e32 v0, 16, v3
	v_mul_f32_e32 v0, 0xbfb8aa3b, v0
	v_exp_f32_e32 v2, v0
	v_and_b32_e32 v0, 0xffff0000, v3
	v_mul_f32_e32 v0, 0xbfb8aa3b, v0
	v_exp_f32_e32 v3, v0
	v_pk_mul_f32 v[4:5], v[6:7], v[4:5]
	v_pk_mul_f32 v[6:7], v[16:17], v[66:67] op_sel_hi:[1,0]
	v_cvt_pk_bf16_f32 v4, v4, v5
	v_pk_add_f32 v[2:3], v[2:3], 1.0 op_sel_hi:[1,0]
	s_nop 0
	v_div_scale_f32 v0, s[2:3], v3, v3, 1.0
	v_rcp_f32_e32 v8, v0
	s_nop 0
	v_fma_f32 v9, -v0, v8, 1.0
	v_fmac_f32_e32 v8, v9, v8
	v_div_scale_f32 v9, vcc, 1.0, v3, 1.0
	v_mul_f32_e32 v10, v9, v8
	v_fma_f32 v11, -v0, v10, v9
	v_fmac_f32_e32 v10, v11, v8
	v_fma_f32 v0, -v0, v10, v9
	v_div_fmas_f32 v0, v0, v8, v10
	v_div_fixup_f32 v3, v0, v3, 1.0
	v_div_scale_f32 v0, s[2:3], v2, v2, 1.0
	v_rcp_f32_e32 v8, v0
	s_mov_b64 s[2:3], 0
	v_fma_f32 v9, -v0, v8, 1.0
	v_fmac_f32_e32 v8, v9, v8
	v_div_scale_f32 v9, vcc, 1.0, v2, 1.0
	v_mul_f32_e32 v10, v9, v8
	v_fma_f32 v11, -v0, v10, v9
	v_fmac_f32_e32 v10, v11, v8
	v_fma_f32 v0, -v0, v10, v9
	v_div_fmas_f32 v0, v0, v8, v10
	v_div_fixup_f32 v2, v0, v2, 1.0
	v_pk_mul_f32 v[2:3], v[6:7], v[2:3]
	s_nop 0
	v_cvt_pk_bf16_f32 v5, v2, v3
	global_store_dwordx2 v[50:51], v[4:5], off offset:240
